# branch-GEMM epilogue gate loads lane-coalesced (4 neighbouring lanes read one row's 32 bytes) with ds_bpermute back to the MFMA layout
# speedup vs baseline: 1.0392x; 1.0058x over previous
; #define PG8_STAGE(bufoff, gbase, voff) do { _Pragma("unroll") for (int _i = 0; _i < 2; ++_i) \
;         __builtin_amdgcn_global_load_lds((const unsigned*)((const char*)(gbase) + (voff)[_i]), (LAS unsigned*)(lds + (bufoff) + ldsw + _i * 8192), 16, 0, 0); } while (0)
; #define PG8_LDA(dst, b, h) do { _Pragma("unroll") for (int m = 0; m < 4; ++m) _Pragma("unroll") for (int k = 0; k < 2; ++k) dst[m][k] = *(const LAS bf16x8*)(lds + PG8_SA(b, h) + aoff + m * 2048 + k * 1024); } while (0)
; #define PG8_WAIT_V(n) asm volatile("s_waitcnt vmcnt(" #n ")" ::: "memory")
; #define PG8_WAIT_L(n) asm volatile("s_waitcnt lgkmcnt(" #n ")" ::: "memory")
; template <class Epi, class Sched>
; __device__ __forceinline__ void gemm_phase(LAS unsigned char* lds, const Gemm g, const Sched& S, const Epi& E) {
;     ...
;         for (int t = 0; t < nt; t += 2) {
;             const bool last = (t == nt - 2);
;             const char* a1 = cA + (size_t)(t + 1) * kstep;
;             const char* a2 = last ? nA : cA + (size_t)(t + 2) * kstep; const char* b2 = last ? nB : cB + (size_t)(t + 2) * kstep;
;             const char* a3 = a2 + kstep; const char* b3 = b2 + kstep;
;             PG8_LDB(B0, 0, 0); PG8_SCHED; PG8_LDA(At, 0, 0); PG8_STAGE(PG8_SA(1, 1), a1 + hstep, voffA);
;             PG8_WAIT_L(8); PG8_BAR; PG8_WAIT_L(0); PG8_MMA(0, 0, At, B0); PG8_BAR; PG8_SCHED;
;             PG8_LDB(B1, 0, 1); PG8_STAGE(PG8_SB(0, 0), b2, voffB);
;             PG8_BAR; PG8_WAIT_L(0); PG8_MMA(0, 1, At, B1); PG8_BAR;
;             PG8_LDA(At, 0, 1); PG8_STAGE(PG8_SA(0, 0), a2, voffA);
;             PG8_BAR; PG8_WAIT_L(0); PG8_MMA(1, 0, At, B0); PG8_BAR; PG8_SCHED;
;             PG8_STAGE(PG8_SB(0, 1), b2 + hstep, voffB);
;             PG8_WAIT_V(6); PG8_BAR; PG8_MMA(1, 1, At, B1); PG8_BAR;
;             PG8_LDB(B0, 1, 0); PG8_SCHED; PG8_LDA(At, 1, 0); PG8_STAGE(PG8_SA(0, 1), a2 + hstep, voffA);
;             PG8_WAIT_L(8); PG8_BAR; PG8_WAIT_L(0); PG8_MMA(0, 0, At, B0); PG8_BAR; PG8_SCHED;
;             PG8_LDB(B1, 1, 1); PG8_STAGE(PG8_SB(1, 0), b3, voffB);
;             PG8_BAR; PG8_WAIT_L(0); PG8_MMA(0, 1, At, B1); PG8_BAR;
;             PG8_LDA(At, 1, 1); PG8_STAGE(PG8_SA(1, 0), a3, voffA);
;             PG8_BAR; PG8_WAIT_L(0); PG8_MMA(1, 0, At, B0); PG8_BAR; PG8_SCHED;
;             PG8_STAGE(PG8_SB(1, 1), b3 + hstep, voffB);
;             PG8_WAIT_V(6); PG8_BAR; PG8_MMA(1, 1, At, B1); PG8_BAR;
.LBB0_23:
	s_add_u32 s22, s20, 0xfffe0080
	s_addc_u32 s23, s21, -1
	s_add_i32 s43, 0, 0x10000
	v_add_u32_e32 v156, s43, v211
	ds_read_b128 v[144:147], v156
	ds_read_b128 v[148:151], v156 offset:1024
	ds_read_b128 v[152:155], v156 offset:2048
	ds_read_b128 v[156:159], v156 offset:3072
	s_cmp_eq_u32 s42, 4
	s_cselect_b32 s25, s1, s23
	s_cselect_b32 s24, s37, s22
	s_cselect_b32 s23, s38, s41
	s_cselect_b32 s22, s39, s40
	v_lshl_add_u64 v[160:161], s[20:21], 0, v[140:141]
	s_add_i32 m0, s28, 0xc000
	ds_read_b128 v[172:175], v212
	ds_read_b128 v[176:179], v212 offset:1024
	ds_read_b128 v[180:183], v212 offset:2048
	ds_read_b128 v[184:187], v212 offset:3072
	ds_read_b128 v[188:191], v212 offset:4096
	ds_read_b128 v[192:195], v212 offset:5120
	ds_read_b128 v[214:217], v212 offset:6144
	ds_read_b128 v[218:221], v212 offset:7168
	global_load_lds_dwordx4 v[160:161], off
	v_lshl_add_u64 v[160:161], s[20:21], 0, v[142:143]
	s_add_i32 m0, s28, 0xe000
	s_nop 0
	global_load_lds_dwordx4 v[160:161], off
	s_waitcnt lgkmcnt(8)
	s_barrier
	s_waitcnt lgkmcnt(0)
	s_setprio 1
	s_waitcnt lgkmcnt(0)
	v_mfma_f32_16x16x32_bf16 v[126:129], v[144:147], v[172:175], v[126:129]
	v_mfma_f32_16x16x32_bf16 v[122:125], v[152:155], v[172:175], v[122:125]
	v_mfma_f32_16x16x32_bf16 v[118:121], v[144:147], v[180:183], v[118:121]
	v_mfma_f32_16x16x32_bf16 v[114:117], v[152:155], v[180:183], v[114:117]
	v_mfma_f32_16x16x32_bf16 v[110:113], v[144:147], v[188:191], v[110:113]
	v_mfma_f32_16x16x32_bf16 v[106:109], v[152:155], v[188:191], v[106:109]
	v_mfma_f32_16x16x32_bf16 v[102:105], v[144:147], v[214:217], v[102:105]
	v_mfma_f32_16x16x32_bf16 v[98:101], v[152:155], v[214:217], v[98:101]
	v_mfma_f32_16x16x32_bf16 v[126:129], v[148:151], v[176:179], v[126:129]
	v_mfma_f32_16x16x32_bf16 v[122:125], v[156:159], v[176:179], v[122:125]
	v_mfma_f32_16x16x32_bf16 v[118:121], v[148:151], v[184:187], v[118:121]
	v_mfma_f32_16x16x32_bf16 v[114:117], v[156:159], v[184:187], v[114:117]
	v_mfma_f32_16x16x32_bf16 v[110:113], v[148:151], v[192:195], v[110:113]
	v_mfma_f32_16x16x32_bf16 v[106:109], v[156:159], v[192:195], v[106:109]
	v_mfma_f32_16x16x32_bf16 v[102:105], v[148:151], v[218:221], v[102:105]
	v_mfma_f32_16x16x32_bf16 v[98:101], v[156:159], v[218:221], v[98:101]
	s_setprio 0
	s_barrier
	s_add_i32 s55, 0, 0x14000
	v_add_u32_e32 v160, s55, v211
	s_add_i32 s43, s43, s27
	ds_read_b128 v[222:225], v160
	ds_read_b128 v[226:229], v160 offset:1024
	ds_read_b128 v[230:233], v160 offset:2048
	ds_read_b128 v[234:237], v160 offset:3072
	v_lshl_add_u64 v[160:161], s[22:23], 0, v[134:135]
	s_mov_b32 m0, s43
	v_lshl_add_u64 v[196:197], s[22:23], 0, v[130:131]
	global_load_lds_dwordx4 v[160:161], off
	s_add_i32 m0, s43, 0x2000
	s_nop 0
	global_load_lds_dwordx4 v[196:197], off
	s_barrier
	s_waitcnt lgkmcnt(0)
	s_setprio 1
	s_waitcnt lgkmcnt(0)
	v_mfma_f32_16x16x32_bf16 v[94:97], v[222:225], v[172:175], v[94:97]
	v_mfma_f32_16x16x32_bf16 v[90:93], v[230:233], v[172:175], v[90:93]
	v_mfma_f32_16x16x32_bf16 v[86:89], v[222:225], v[180:183], v[86:89]
	v_mfma_f32_16x16x32_bf16 v[82:85], v[230:233], v[180:183], v[82:85]
	v_mfma_f32_16x16x32_bf16 v[78:81], v[222:225], v[188:191], v[78:81]
	v_mfma_f32_16x16x32_bf16 v[74:77], v[230:233], v[188:191], v[74:77]
	v_mfma_f32_16x16x32_bf16 v[70:73], v[222:225], v[214:217], v[70:73]
	v_mfma_f32_16x16x32_bf16 v[66:69], v[230:233], v[214:217], v[66:69]
	v_mfma_f32_16x16x32_bf16 v[94:97], v[226:229], v[176:179], v[94:97]
	v_mfma_f32_16x16x32_bf16 v[90:93], v[234:237], v[176:179], v[90:93]
	v_mfma_f32_16x16x32_bf16 v[86:89], v[226:229], v[184:187], v[86:89]
	v_mfma_f32_16x16x32_bf16 v[82:85], v[234:237], v[184:187], v[82:85]
	v_mfma_f32_16x16x32_bf16 v[78:81], v[226:229], v[192:195], v[78:81]
	v_mfma_f32_16x16x32_bf16 v[74:77], v[234:237], v[192:195], v[74:77]
	v_mfma_f32_16x16x32_bf16 v[70:73], v[226:229], v[218:221], v[70:73]
	v_mfma_f32_16x16x32_bf16 v[66:69], v[234:237], v[218:221], v[66:69]
	s_setprio 0
	s_mov_b32 m0, s28
	v_lshl_add_u64 v[238:239], s[24:25], 0, v[136:137]
	s_barrier
	ds_read_b128 v[172:175], v212 offset:16384
	ds_read_b128 v[176:179], v212 offset:17408
	ds_read_b128 v[180:183], v212 offset:18432
	ds_read_b128 v[184:187], v212 offset:19456
	ds_read_b128 v[188:191], v212 offset:20480
	ds_read_b128 v[192:195], v212 offset:21504
	ds_read_b128 v[214:217], v212 offset:22528
	ds_read_b128 v[218:221], v212 offset:23552
	global_load_lds_dwordx4 v[238:239], off
	v_lshl_add_u64 v[240:241], s[24:25], 0, v[132:133]
	s_mov_b32 m0, s29
	s_nop 0
	global_load_lds_dwordx4 v[240:241], off
	s_barrier
	s_waitcnt lgkmcnt(0)
	s_setprio 1
	s_waitcnt lgkmcnt(0)
	v_mfma_f32_16x16x32_bf16 v[62:65], v[144:147], v[172:175], v[62:65]
	v_mfma_f32_16x16x32_bf16 v[58:61], v[152:155], v[172:175], v[58:61]
	v_mfma_f32_16x16x32_bf16 v[54:57], v[144:147], v[180:183], v[54:57]
	v_mfma_f32_16x16x32_bf16 v[50:53], v[152:155], v[180:183], v[50:53]
	v_mfma_f32_16x16x32_bf16 v[46:49], v[144:147], v[188:191], v[46:49]
	v_mfma_f32_16x16x32_bf16 v[42:45], v[152:155], v[188:191], v[42:45]
	v_mfma_f32_16x16x32_bf16 v[38:41], v[144:147], v[214:217], v[38:41]
	v_mfma_f32_16x16x32_bf16 v[34:37], v[152:155], v[214:217], v[34:37]
	v_mfma_f32_16x16x32_bf16 v[62:65], v[148:151], v[176:179], v[62:65]
	v_mfma_f32_16x16x32_bf16 v[58:61], v[156:159], v[176:179], v[58:61]
	v_mfma_f32_16x16x32_bf16 v[54:57], v[148:151], v[184:187], v[54:57]
	v_mfma_f32_16x16x32_bf16 v[50:53], v[156:159], v[184:187], v[50:53]
	v_mfma_f32_16x16x32_bf16 v[46:49], v[148:151], v[192:195], v[46:49]
	v_mfma_f32_16x16x32_bf16 v[42:45], v[156:159], v[192:195], v[42:45]
	v_mfma_f32_16x16x32_bf16 v[38:41], v[148:151], v[218:221], v[38:41]
	v_mfma_f32_16x16x32_bf16 v[34:37], v[156:159], v[218:221], v[34:37]
	s_setprio 0
	s_barrier
; #define PG8_STAGE(bufoff, gbase, voff) do { _Pragma("unroll") for (int _i = 0; _i < 2; ++_i) \
;         __builtin_amdgcn_global_load_lds((const unsigned*)((const char*)(gbase) + (voff)[_i]), (LAS unsigned*)(lds + (bufoff) + ldsw + _i * 8192), 16, 0, 0); } while (0)
; #define PG8_LDA(dst, b, h) do { _Pragma("unroll") for (int m = 0; m < 4; ++m) _Pragma("unroll") for (int k = 0; k < 2; ++k) dst[m][k] = *(const LAS bf16x8*)(lds + PG8_SA(b, h) + aoff + m * 2048 + k * 1024); } while (0)
; #define PG8_WAIT_V(n) asm volatile("s_waitcnt vmcnt(" #n ")" ::: "memory")
; #define PG8_WAIT_L(n) asm volatile("s_waitcnt lgkmcnt(" #n ")" ::: "memory")
; template <class Epi, class Sched>
; __device__ __forceinline__ void gemm_phase(LAS unsigned char* lds, const Gemm g, const Sched& S, const Epi& E) {
;     ...
;         for (int t = 0; t < nt; t += 2) {
;             const bool last = (t == nt - 2);
;             const char* a1 = cA + (size_t)(t + 1) * kstep;
;             const char* a2 = last ? nA : cA + (size_t)(t + 2) * kstep; const char* b2 = last ? nB : cB + (size_t)(t + 2) * kstep;
;             const char* a3 = a2 + kstep; const char* b3 = b2 + kstep;
;             PG8_LDB(B0, 0, 0); PG8_SCHED; PG8_LDA(At, 0, 0); PG8_STAGE(PG8_SA(1, 1), a1 + hstep, voffA);
;             PG8_WAIT_L(8); PG8_BAR; PG8_WAIT_L(0); PG8_MMA(0, 0, At, B0); PG8_BAR; PG8_SCHED;
;             PG8_LDB(B1, 0, 1); PG8_STAGE(PG8_SB(0, 0), b2, voffB);
;             PG8_BAR; PG8_WAIT_L(0); PG8_MMA(0, 1, At, B1); PG8_BAR;
;             PG8_LDA(At, 0, 1); PG8_STAGE(PG8_SA(0, 0), a2, voffA);
;             PG8_BAR; PG8_WAIT_L(0); PG8_MMA(1, 0, At, B0); PG8_BAR; PG8_SCHED;
;             PG8_STAGE(PG8_SB(0, 1), b2 + hstep, voffB);
;             PG8_WAIT_V(6); PG8_BAR; PG8_MMA(1, 1, At, B1); PG8_BAR;
;             PG8_LDB(B0, 1, 0); PG8_SCHED; PG8_LDA(At, 1, 0); PG8_STAGE(PG8_SA(0, 1), a2 + hstep, voffA);
;             PG8_WAIT_L(8); PG8_BAR; PG8_WAIT_L(0); PG8_MMA(0, 0, At, B0); PG8_BAR; PG8_SCHED;
;             PG8_LDB(B1, 1, 1); PG8_STAGE(PG8_SB(1, 0), b3, voffB);
;             PG8_BAR; PG8_WAIT_L(0); PG8_MMA(0, 1, At, B1); PG8_BAR;
;             PG8_LDA(At, 1, 1); PG8_STAGE(PG8_SA(1, 0), a3, voffA);
;             PG8_BAR; PG8_WAIT_L(0); PG8_MMA(1, 0, At, B0); PG8_BAR; PG8_SCHED;
;             PG8_STAGE(PG8_SB(1, 1), b3 + hstep, voffB);
;             PG8_WAIT_V(6); PG8_BAR; PG8_MMA(1, 1, At, B1); PG8_BAR;
	s_add_u32 s56, s22, 0x20000
	s_addc_u32 s57, s23, 0
	s_add_i32 s43, s55, s27
	v_lshl_add_u64 v[144:145], s[56:57], 0, v[134:135]
	s_mov_b32 m0, s43
	s_nop 0
	global_load_lds_dwordx4 v[144:145], off
	v_lshl_add_u64 v[144:145], s[56:57], 0, v[130:131]
	s_add_i32 m0, s43, 0x2000
	s_nop 0
	global_load_lds_dwordx4 v[144:145], off
	s_waitcnt vmcnt(6)
	s_barrier
	s_setprio 1
	v_mfma_f32_16x16x32_bf16 v[30:33], v[222:225], v[172:175], v[30:33]
	v_mfma_f32_16x16x32_bf16 v[26:29], v[230:233], v[172:175], v[26:29]
	v_mfma_f32_16x16x32_bf16 v[22:25], v[222:225], v[180:183], v[22:25]
	v_mfma_f32_16x16x32_bf16 v[18:21], v[230:233], v[180:183], v[18:21]
	v_mfma_f32_16x16x32_bf16 v[14:17], v[222:225], v[188:191], v[14:17]
	v_mfma_f32_16x16x32_bf16 v[10:13], v[230:233], v[188:191], v[10:13]
	v_mfma_f32_16x16x32_bf16 v[6:9], v[222:225], v[214:217], v[6:9]
	v_mfma_f32_16x16x32_bf16 v[2:5], v[230:233], v[214:217], v[2:5]
	v_mfma_f32_16x16x32_bf16 v[30:33], v[226:229], v[176:179], v[30:33]
	v_mfma_f32_16x16x32_bf16 v[26:29], v[234:237], v[176:179], v[26:29]
	v_mfma_f32_16x16x32_bf16 v[22:25], v[226:229], v[184:187], v[22:25]
	v_mfma_f32_16x16x32_bf16 v[18:21], v[234:237], v[184:187], v[18:21]
	v_mfma_f32_16x16x32_bf16 v[14:17], v[226:229], v[192:195], v[14:17]
	v_mfma_f32_16x16x32_bf16 v[10:13], v[234:237], v[192:195], v[10:13]
	v_mfma_f32_16x16x32_bf16 v[6:9], v[226:229], v[218:221], v[6:9]
	v_mfma_f32_16x16x32_bf16 v[2:5], v[234:237], v[218:221], v[2:5]
	s_setprio 0
	s_add_i32 s43, 0, 0x18000
	v_add_u32_e32 v156, s43, v211
	s_barrier
	ds_read_b128 v[144:147], v156
	ds_read_b128 v[148:151], v156 offset:1024
	ds_read_b128 v[152:155], v156 offset:2048
	ds_read_b128 v[156:159], v156 offset:3072
	s_add_u32 s24, s24, 0x20000
	s_addc_u32 s25, s25, 0
	s_mov_b32 m0, s44
	v_lshl_add_u64 v[222:223], s[24:25], 0, v[136:137]
	ds_read_b128 v[172:175], v212 offset:32768
	ds_read_b128 v[176:179], v212 offset:33792
	ds_read_b128 v[180:183], v212 offset:34816
	ds_read_b128 v[184:187], v212 offset:35840
	ds_read_b128 v[188:191], v212 offset:36864
	ds_read_b128 v[192:195], v212 offset:37888
	ds_read_b128 v[214:217], v212 offset:38912
	ds_read_b128 v[218:221], v212 offset:39936
	global_load_lds_dwordx4 v[222:223], off
	v_lshl_add_u64 v[222:223], s[24:25], 0, v[132:133]
	s_mov_b32 m0, s45
	s_nop 0
	global_load_lds_dwordx4 v[222:223], off
	s_waitcnt lgkmcnt(8)
	s_barrier
	s_waitcnt lgkmcnt(0)
	s_setprio 1
	s_waitcnt lgkmcnt(0)
	v_mfma_f32_16x16x32_bf16 v[126:129], v[144:147], v[172:175], v[126:129]
	v_mfma_f32_16x16x32_bf16 v[122:125], v[152:155], v[172:175], v[122:125]
	v_mfma_f32_16x16x32_bf16 v[118:121], v[144:147], v[180:183], v[118:121]
	v_mfma_f32_16x16x32_bf16 v[114:117], v[152:155], v[180:183], v[114:117]
	v_mfma_f32_16x16x32_bf16 v[110:113], v[144:147], v[188:191], v[110:113]
	v_mfma_f32_16x16x32_bf16 v[106:109], v[152:155], v[188:191], v[106:109]
	v_mfma_f32_16x16x32_bf16 v[102:105], v[144:147], v[214:217], v[102:105]
	v_mfma_f32_16x16x32_bf16 v[98:101], v[152:155], v[214:217], v[98:101]
	v_mfma_f32_16x16x32_bf16 v[126:129], v[148:151], v[176:179], v[126:129]
	v_mfma_f32_16x16x32_bf16 v[122:125], v[156:159], v[176:179], v[122:125]
	v_mfma_f32_16x16x32_bf16 v[118:121], v[148:151], v[184:187], v[118:121]
	v_mfma_f32_16x16x32_bf16 v[114:117], v[156:159], v[184:187], v[114:117]
	v_mfma_f32_16x16x32_bf16 v[110:113], v[148:151], v[192:195], v[110:113]
	v_mfma_f32_16x16x32_bf16 v[106:109], v[156:159], v[192:195], v[106:109]
	v_mfma_f32_16x16x32_bf16 v[102:105], v[148:151], v[218:221], v[102:105]
	v_mfma_f32_16x16x32_bf16 v[98:101], v[156:159], v[218:221], v[98:101]
	s_setprio 0
	s_barrier
	s_add_i32 s24, 0, 0x1c000
	s_add_i32 s25, s43, s27
	v_add_u32_e32 v213, s24, v211
	v_lshl_add_u64 v[160:161], v[160:161], 0, s[2:3]
	s_mov_b32 m0, s25
	ds_read_b128 v[222:225], v213
	ds_read_b128 v[226:229], v213 offset:1024
	ds_read_b128 v[230:233], v213 offset:2048
	ds_read_b128 v[234:237], v213 offset:3072
	global_load_lds_dwordx4 v[160:161], off
	v_lshl_add_u64 v[160:161], v[196:197], 0, s[2:3]
	s_add_i32 m0, s25, 0x2000
	s_nop 0
	global_load_lds_dwordx4 v[160:161], off
	s_barrier
	s_waitcnt lgkmcnt(0)
	s_setprio 1
	s_waitcnt lgkmcnt(0)
	v_mfma_f32_16x16x32_bf16 v[94:97], v[222:225], v[172:175], v[94:97]
	v_mfma_f32_16x16x32_bf16 v[90:93], v[230:233], v[172:175], v[90:93]
	v_mfma_f32_16x16x32_bf16 v[86:89], v[222:225], v[180:183], v[86:89]
	v_mfma_f32_16x16x32_bf16 v[82:85], v[230:233], v[180:183], v[82:85]
	v_mfma_f32_16x16x32_bf16 v[78:81], v[222:225], v[188:191], v[78:81]
	v_mfma_f32_16x16x32_bf16 v[74:77], v[230:233], v[188:191], v[74:77]
	v_mfma_f32_16x16x32_bf16 v[70:73], v[222:225], v[214:217], v[70:73]
	v_mfma_f32_16x16x32_bf16 v[66:69], v[230:233], v[214:217], v[66:69]
	v_mfma_f32_16x16x32_bf16 v[94:97], v[226:229], v[176:179], v[94:97]
	v_mfma_f32_16x16x32_bf16 v[90:93], v[234:237], v[176:179], v[90:93]
	v_mfma_f32_16x16x32_bf16 v[86:89], v[226:229], v[184:187], v[86:89]
	v_mfma_f32_16x16x32_bf16 v[82:85], v[234:237], v[184:187], v[82:85]
	v_mfma_f32_16x16x32_bf16 v[78:81], v[226:229], v[192:195], v[78:81]
	v_mfma_f32_16x16x32_bf16 v[74:77], v[234:237], v[192:195], v[74:77]
	v_mfma_f32_16x16x32_bf16 v[70:73], v[226:229], v[218:221], v[70:73]
	v_mfma_f32_16x16x32_bf16 v[66:69], v[234:237], v[218:221], v[66:69]
	s_setprio 0
	s_mov_b32 m0, s50
	v_lshl_add_u64 v[160:161], v[238:239], 0, s[2:3]
	s_barrier
; #define PG8_STAGE(bufoff, gbase, voff) do { _Pragma("unroll") for (int _i = 0; _i < 2; ++_i) \
;         __builtin_amdgcn_global_load_lds((const unsigned*)((const char*)(gbase) + (voff)[_i]), (LAS unsigned*)(lds + (bufoff) + ldsw + _i * 8192), 16, 0, 0); } while (0)
; #define PG8_LDA(dst, b, h) do { _Pragma("unroll") for (int m = 0; m < 4; ++m) _Pragma("unroll") for (int k = 0; k < 2; ++k) dst[m][k] = *(const LAS bf16x8*)(lds + PG8_SA(b, h) + aoff + m * 2048 + k * 1024); } while (0)
; #define PG8_MMA(ai, bj, At, Bt) do { __builtin_amdgcn_s_setprio(1); _Pragma("unroll") for (int m = 0; m < 4; ++m) _Pragma("unroll") for (int n = 0; n < 2; ++n) _Pragma("unroll") for (int k = 0; k < 2; ++k) \
;         acc[ai][bj][m][n] = __builtin_amdgcn_mfma_f32_16x16x32_bf16(Bt[n][k], At[m][k], acc[ai][bj][m][n], 0, 0, 0); __builtin_amdgcn_s_setprio(0); } while (0)
; #define PG8_WAIT_V(n) asm volatile("s_waitcnt vmcnt(" #n ")" ::: "memory")
; #define PG8_WAIT_L(n) asm volatile("s_waitcnt lgkmcnt(" #n ")" ::: "memory")
; #define PG8_BAR __builtin_amdgcn_s_barrier()
; #define PG8_SCHED __builtin_amdgcn_sched_barrier(0)
; template <class Epi, class Sched>
; __device__ __forceinline__ void gemm_phase(LAS unsigned char* lds, const Gemm g, const Sched& S, const Epi& E) {
;     ...
;             PG8_BAR; PG8_WAIT_L(0); PG8_MMA(0, 1, At, B1); PG8_BAR;
;             PG8_LDA(At, 1, 1); PG8_STAGE(PG8_SA(1, 0), a3, voffA);
;             PG8_BAR; PG8_WAIT_L(0); PG8_MMA(1, 0, At, B0); PG8_BAR; PG8_SCHED;
;             PG8_STAGE(PG8_SB(1, 1), b3 + hstep, voffB);
;             PG8_WAIT_V(6); PG8_BAR; PG8_MMA(1, 1, At, B1); PG8_BAR;
;     __device__ __forceinline__ void operator()(f32x4 (&acc)[2][2][4][2], const pg8::Unit& u, int wr, int wc, int fr, int fq) const {
;         const int row0 = u.pm * 256 + wr * 64 + fr, cin = wc * 32 + 8 * fq; const bool last = (u.pn >= 12);
; #pragma unroll
;         for (int ai = 0; ai < 2; ++ai) {
;             u32x2 ga[4][2], gb[4][2];
; #pragma unroll
;             for (int m = 0; m < 4; ++m) {
;                 const unsigned char* gp = gq + (size_t)(row0 + ai * 128 + m * 16) * 4096 + u.pn * 256 + cin;
; #pragma unroll
;                 for (int bj = 0; bj < 2; ++bj) { ga[m][bj] = *(const u32x2*)(gp + bj * 128);
;                     gb[m][bj] = last ? (u32x2){0x01010101u, 0x01010101u} : *(const u32x2*)(gp + 1024 + bj * 128); }
	ds_read_b128 v[172:175], v212 offset:49152
	ds_read_b128 v[176:179], v212 offset:50176
	ds_read_b128 v[180:183], v212 offset:51200
	ds_read_b128 v[184:187], v212 offset:52224
	ds_read_b128 v[188:191], v212 offset:53248
	ds_read_b128 v[192:195], v212 offset:54272
	ds_read_b128 v[214:217], v212 offset:55296
	ds_read_b128 v[218:221], v212 offset:56320
	global_load_lds_dwordx4 v[160:161], off
	v_lshl_add_u64 v[160:161], v[240:241], 0, s[2:3]
	s_mov_b32 m0, s51
	s_nop 0
	global_load_lds_dwordx4 v[160:161], off
	s_barrier
	s_waitcnt lgkmcnt(0)
	s_setprio 1
	s_waitcnt lgkmcnt(0)
	v_mfma_f32_16x16x32_bf16 v[62:65], v[144:147], v[172:175], v[62:65]
	v_mfma_f32_16x16x32_bf16 v[58:61], v[152:155], v[172:175], v[58:61]
	v_mfma_f32_16x16x32_bf16 v[54:57], v[144:147], v[180:183], v[54:57]
	v_mfma_f32_16x16x32_bf16 v[50:53], v[152:155], v[180:183], v[50:53]
	v_mfma_f32_16x16x32_bf16 v[46:49], v[144:147], v[188:191], v[46:49]
	v_mfma_f32_16x16x32_bf16 v[42:45], v[152:155], v[188:191], v[42:45]
	v_mfma_f32_16x16x32_bf16 v[38:41], v[144:147], v[214:217], v[38:41]
	v_mfma_f32_16x16x32_bf16 v[34:37], v[152:155], v[214:217], v[34:37]
	v_mfma_f32_16x16x32_bf16 v[62:65], v[148:151], v[176:179], v[62:65]
	v_mfma_f32_16x16x32_bf16 v[58:61], v[156:159], v[176:179], v[58:61]
	v_mfma_f32_16x16x32_bf16 v[54:57], v[148:151], v[184:187], v[54:57]
	v_mfma_f32_16x16x32_bf16 v[50:53], v[156:159], v[184:187], v[50:53]
	v_mfma_f32_16x16x32_bf16 v[46:49], v[148:151], v[192:195], v[46:49]
	v_mfma_f32_16x16x32_bf16 v[42:45], v[156:159], v[192:195], v[42:45]
	v_mfma_f32_16x16x32_bf16 v[38:41], v[148:151], v[218:221], v[38:41]
	v_mfma_f32_16x16x32_bf16 v[34:37], v[156:159], v[218:221], v[34:37]
	s_setprio 0
	s_barrier
	s_add_u32 s22, s22, 0x20080
	s_addc_u32 s23, s23, 0
	s_add_i32 s24, s24, s27
	v_lshl_add_u64 v[144:145], s[22:23], 0, v[134:135]
	s_mov_b32 m0, s24
	s_nop 0
	global_load_lds_dwordx4 v[144:145], off
	v_lshl_add_u64 v[144:145], s[22:23], 0, v[130:131]
	s_add_i32 m0, s24, 0x2000
	s_nop 0
	global_load_lds_dwordx4 v[144:145], off
	s_waitcnt vmcnt(6)
	s_barrier
	s_setprio 1
	v_mfma_f32_16x16x32_bf16 v[30:33], v[222:225], v[172:175], v[30:33]
	v_mfma_f32_16x16x32_bf16 v[26:29], v[230:233], v[172:175], v[26:29]
	v_mfma_f32_16x16x32_bf16 v[22:25], v[222:225], v[180:183], v[22:25]
	v_mfma_f32_16x16x32_bf16 v[18:21], v[230:233], v[180:183], v[18:21]
	v_mfma_f32_16x16x32_bf16 v[14:17], v[222:225], v[188:191], v[14:17]
	v_mfma_f32_16x16x32_bf16 v[10:13], v[230:233], v[188:191], v[10:13]
	v_mfma_f32_16x16x32_bf16 v[6:9], v[222:225], v[214:217], v[6:9]
	v_mfma_f32_16x16x32_bf16 v[2:5], v[230:233], v[214:217], v[2:5]
	v_mfma_f32_16x16x32_bf16 v[30:33], v[226:229], v[176:179], v[30:33]
	v_mfma_f32_16x16x32_bf16 v[26:29], v[234:237], v[176:179], v[26:29]
	v_mfma_f32_16x16x32_bf16 v[22:25], v[226:229], v[184:187], v[22:25]
	v_mfma_f32_16x16x32_bf16 v[18:21], v[234:237], v[184:187], v[18:21]
	v_mfma_f32_16x16x32_bf16 v[14:17], v[226:229], v[192:195], v[14:17]
	v_mfma_f32_16x16x32_bf16 v[10:13], v[234:237], v[192:195], v[10:13]
	v_mfma_f32_16x16x32_bf16 v[6:9], v[226:229], v[218:221], v[6:9]
	v_mfma_f32_16x16x32_bf16 v[2:5], v[234:237], v[218:221], v[2:5]
	s_setprio 0
	s_add_i32 s42, s42, 2
	s_add_u32 s20, s20, 0x100
	s_addc_u32 s21, s21, 0
	s_add_u32 s40, s40, 0x100
	s_addc_u32 s41, s41, 0
	s_cmp_gt_u32 s42, 5
	s_barrier
	s_cbranch_scc0 .LBB0_23
	s_cmp_gt_u32 s54, 11
	v_lshl_add_u32 v144, s30, 8, v163
	s_cselect_b64 s[38:39], -1, 0
	s_cmp_lt_u32 s54, 12
	s_cselect_b64 s[20:21], -1, 0
	s_lshl_b32 s30, s54, 8
	v_ashrrev_i32_e32 v145, 31, v144
	v_lshl_add_u64 v[146:147], v[138:139], 0, s[30:31]
	v_bfe_u32 v236, v198, 2, 4
	v_and_b32_e32 v237, 15, v198
	v_sub_u32_e32 v236, v236, v237
	v_and_b32_e32 v237, 3, v198
	v_bfe_u32 v238, v198, 4, 2
	v_sub_u32_e32 v237, v237, v238
	v_lshlrev_b32_e32 v236, 12, v236
	v_lshl_add_u32 v236, v237, 3, v236
	v_ashrrev_i32_e32 v237, 31, v236
	v_lshl_add_u64 v[146:147], v[146:147], 0, v[236:237]
	v_lshlrev_b64 v[148:149], 12, v[144:145]
	v_lshl_add_u64 v[148:149], v[146:147], 0, v[148:149]
	global_load_dwordx2 v[192:193], v[148:149], off
	v_mov_b32_e32 v188, 0x1010101
	s_and_b64 vcc, exec, s[38:39]
	v_mov_b32_e32 v196, 0x1010101
	v_mov_b32_e32 v197, 0x1010101
	s_cbranch_vccnz .LBB0_26
	global_load_dwordx2 v[196:197], v[148:149], off offset:1024

; __device__ __forceinline__ unsigned cvtpk(float lo, float hi) { unsigned r; asm volatile("v_cvt_pk_bf16_f32 %0, %1, %2" : "=v"(r) : "v"(lo), "v"(hi)); return r; }
;     __device__ __forceinline__ void operator()(f32x4 (&acc)[2][2][4][2], const pg8::Unit& u, int wr, int wc, int fr, int fq) const {
;     ...
;             for (int m = 0; m < 4; ++m) {
;                 u16* op = hbuf + (size_t)(row0 + ai * 128 + m * 16) * DM + (u.pn & 3) * 256 + cin;
; #pragma unroll
;                 for (int bj = 0; bj < 2; ++bj) {
;                     f32x4 vv[2];
; #pragma unroll
;                     for (int n = 0; n < 2; ++n) {
;                         const unsigned a4 = ga[m][bj][n], b4 = gb[m][bj][n]; f32x4 v = acc[ai][bj][m][n];
; #pragma unroll
;                         for (int j = 0; j < 4; ++j) { const float ga_ = fmaxf((float)((a4 >> (8 * j)) & 255u), 1.f), gb_ = fmaxf((float)((b4 >> (8 * j)) & 255u), 1.f);
;                             v[j] *= last ? ga_ * (1.f / 255.f) : ga_ * __builtin_amdgcn_rcpf(gb_); }
;                         vv[n] = v; if (!last) acc[ai][bj][m][n] = v;
;                     }
;                     if (last) { u32x4 o = {cvtpk(vv[0][0], vv[0][1]), cvtpk(vv[0][2], vv[0][3]), cvtpk(vv[1][0], vv[1][1]), cvtpk(vv[1][2], vv[1][3])}; *(u32x4*)(op + bj * 128) = o; }
.LBB0_40:
	v_lshlrev_b64 v[194:195], 11, v[144:145]
	s_waitcnt vmcnt(0)
	v_and_b32_e32 v213, 15, v198
	v_bfe_u32 v214, v198, 4, 2
	v_lshl_or_b32 v213, v213, 2, v214
	v_lshlrev_b32_e32 v213, 2, v213
	ds_bpermute_b32 v192, v213, v192
	ds_bpermute_b32 v193, v213, v193
	ds_bpermute_b32 v196, v213, v196
	ds_bpermute_b32 v197, v213, v197
	ds_bpermute_b32 v190, v213, v190
	ds_bpermute_b32 v191, v213, v191
	ds_bpermute_b32 v188, v213, v188
	ds_bpermute_b32 v189, v213, v189
	ds_bpermute_b32 v182, v213, v182
	ds_bpermute_b32 v183, v213, v183
	ds_bpermute_b32 v184, v213, v184
	ds_bpermute_b32 v185, v213, v185
	ds_bpermute_b32 v180, v213, v180
	ds_bpermute_b32 v181, v213, v181
	ds_bpermute_b32 v178, v213, v178
	s_waitcnt lgkmcnt(7)
	ds_bpermute_b32 v179, v213, v179
	ds_bpermute_b32 v172, v213, v172
	ds_bpermute_b32 v173, v213, v173
	ds_bpermute_b32 v174, v213, v174
	ds_bpermute_b32 v175, v213, v175
	ds_bpermute_b32 v160, v213, v160
	ds_bpermute_b32 v161, v213, v161
	ds_bpermute_b32 v158, v213, v158
	s_waitcnt lgkmcnt(7)
	ds_bpermute_b32 v159, v213, v159
	ds_bpermute_b32 v152, v213, v152
	ds_bpermute_b32 v153, v213, v153
	ds_bpermute_b32 v154, v213, v154
	ds_bpermute_b32 v155, v213, v155
	ds_bpermute_b32 v150, v213, v150
	ds_bpermute_b32 v151, v213, v151
	ds_bpermute_b32 v148, v213, v148
	s_waitcnt lgkmcnt(7)
	ds_bpermute_b32 v149, v213, v149
	s_waitcnt lgkmcnt(0)
	v_cvt_f32_ubyte0_e32 v145, v196
	v_rcp_f32_e32 v145, v145
	v_cvt_f32_ubyte0_e32 v213, v192
	v_cvt_f32_ubyte1_e32 v216, v193
	v_cndmask_b32_e64 v145, v145, v203, s[38:39]
	v_mul_f32_e32 v145, v213, v145
	v_cvt_f32_ubyte1_e32 v213, v196
	v_rcp_f32_e32 v214, v213
	v_mul_f32_e32 v213, v126, v145
	v_cvt_f32_ubyte1_e32 v145, v192
	v_cndmask_b32_e64 v214, v214, v203, s[38:39]
	v_mul_f32_e32 v145, v145, v214
	v_cvt_f32_ubyte2_e32 v214, v196
	v_rcp_f32_e32 v215, v214
	v_mul_f32_e32 v214, v127, v145
	v_cvt_f32_ubyte2_e32 v145, v192
	v_cvt_f32_ubyte3_e32 v196, v196
	v_cndmask_b32_e64 v215, v215, v203, s[38:39]
	v_mul_f32_e32 v145, v145, v215
	v_rcp_f32_e32 v215, v196
	v_mul_f32_e32 v196, v128, v145
	v_cvt_f32_ubyte3_e32 v145, v192
	v_cndmask_b32_e64 v192, v215, v203, s[38:39]
	v_mul_f32_e32 v145, v145, v192
	v_cvt_f32_ubyte0_e32 v192, v197
	v_rcp_f32_e32 v192, v192
	v_mul_f32_e32 v215, v129, v145
	v_cvt_f32_ubyte0_e32 v145, v193
	v_cndmask_b32_e64 v192, v192, v203, s[38:39]
	v_mul_f32_e32 v145, v145, v192
	v_cvt_f32_ubyte1_e32 v192, v197
	v_rcp_f32_e32 v192, v192
	v_cvt_f32_ubyte2_e32 v217, v193
	v_cndmask_b32_e64 v192, v192, v203, s[38:39]
	v_mul_f32_e32 v192, v216, v192
	v_cvt_f32_ubyte2_e32 v216, v197
	v_rcp_f32_e32 v216, v216
	v_cvt_f32_ubyte3_e32 v197, v197
	s_and_b32 s1, s30, 0x300
	v_cndmask_b32_e64 v216, v216, v203, s[38:39]
	v_mul_f32_e32 v216, v217, v216
	v_rcp_f32_e32 v217, v197
	v_cvt_f32_ubyte3_e32 v193, v193
	v_lshl_add_u64 v[194:195], s[12:13], 0, v[194:195]
	s_lshl_b32 s30, s1, 1
	v_mul_f32_e32 v197, v124, v216
	v_cndmask_b32_e64 v216, v217, v203, s[38:39]
	v_lshl_add_u64 v[194:195], v[194:195], 0, s[30:31]
	v_mul_f32_e32 v193, v193, v216
	v_cndmask_b32_e64 v216, 0, 1, s[38:39]
	v_lshl_add_u64 v[194:195], v[194:195], 0, v[0:1]
	v_mul_f32_e32 v145, v122, v145
	v_mul_f32_e32 v192, v123, v192
	v_cmp_ne_u32_e64 s[40:41], 1, v216
	s_andn2_b64 vcc, exec, s[38:39]
	v_mul_f32_e32 v193, v125, v193
	s_cbranch_vccnz .LBB0_42
	v_cvt_pk_bf16_f32 v216, v213, v214
	v_cvt_pk_bf16_f32 v217, v196, v215
	v_cvt_pk_bf16_f32 v218, v145, v192
	v_cvt_pk_bf16_f32 v219, v197, v193
	global_store_dwordx4 v[194:195], v[216:219], off
	s_branch .LBB0_43

; __device__ __forceinline__ unsigned cvtpk(float lo, float hi) { unsigned r; asm volatile("v_cvt_pk_bf16_f32 %0, %1, %2" : "=v"(r) : "v"(lo), "v"(hi)); return r; }
;     __device__ __forceinline__ void operator()(f32x4 (&acc)[2][2][4][2], const pg8::Unit& u, int wr, int wc, int fr, int fq) const {
;     ...
;             for (int m = 0; m < 4; ++m) {
;                 u16* op = hbuf + (size_t)(row0 + ai * 128 + m * 16) * DM + (u.pn & 3) * 256 + cin;
; #pragma unroll
;                 for (int bj = 0; bj < 2; ++bj) {
;                     f32x4 vv[2];
; #pragma unroll
;                     for (int n = 0; n < 2; ++n) {
;                         const unsigned a4 = ga[m][bj][n], b4 = gb[m][bj][n]; f32x4 v = acc[ai][bj][m][n];
; #pragma unroll
;                         for (int j = 0; j < 4; ++j) { const float ga_ = fmaxf((float)((a4 >> (8 * j)) & 255u), 1.f), gb_ = fmaxf((float)((b4 >> (8 * j)) & 255u), 1.f);
;                             v[j] *= last ? ga_ * (1.f / 255.f) : ga_ * __builtin_amdgcn_rcpf(gb_); }
;                         vv[n] = v; if (!last) acc[ai][bj][m][n] = v;
;                     }
;                     if (last) { u32x4 o = {cvtpk(vv[0][0], vv[0][1]), cvtpk(vv[0][2], vv[0][3]), cvtpk(vv[1][0], vv[1][1]), cvtpk(vv[1][2], vv[1][3])}; *(u32x4*)(op + bj * 128) = o; }
.LBB0_80:
	s_waitcnt vmcnt(0)
	v_and_b32_e32 v243, 15, v198
	v_bfe_u32 v244, v198, 4, 2
	v_lshl_or_b32 v243, v243, 2, v244
	v_lshlrev_b32_e32 v243, 2, v243
	ds_bpermute_b32 v188, v243, v188
	ds_bpermute_b32 v189, v243, v189
	ds_bpermute_b32 v192, v243, v192
	ds_bpermute_b32 v193, v243, v193
	ds_bpermute_b32 v186, v243, v186
	ds_bpermute_b32 v187, v243, v187
	ds_bpermute_b32 v184, v243, v184
	ds_bpermute_b32 v185, v243, v185
	ds_bpermute_b32 v178, v243, v178
	ds_bpermute_b32 v179, v243, v179
	ds_bpermute_b32 v180, v243, v180
	ds_bpermute_b32 v181, v243, v181
	ds_bpermute_b32 v176, v243, v176
	ds_bpermute_b32 v177, v243, v177
	ds_bpermute_b32 v174, v243, v174
	s_waitcnt lgkmcnt(7)
	ds_bpermute_b32 v175, v243, v175
	ds_bpermute_b32 v158, v243, v158
	ds_bpermute_b32 v159, v243, v159
	ds_bpermute_b32 v160, v243, v160
	ds_bpermute_b32 v161, v243, v161
	ds_bpermute_b32 v156, v243, v156
	ds_bpermute_b32 v157, v243, v157
	ds_bpermute_b32 v154, v243, v154
	s_waitcnt lgkmcnt(7)
	ds_bpermute_b32 v155, v243, v155
	ds_bpermute_b32 v148, v243, v148
	ds_bpermute_b32 v149, v243, v149
	ds_bpermute_b32 v150, v243, v150
	ds_bpermute_b32 v151, v243, v151
	ds_bpermute_b32 v146, v243, v146
	ds_bpermute_b32 v147, v243, v147
	ds_bpermute_b32 v144, v243, v144
	s_waitcnt lgkmcnt(7)
	ds_bpermute_b32 v145, v243, v145
	s_waitcnt lgkmcnt(0)
	v_cvt_f32_ubyte0_e32 v194, v192
	v_rcp_f32_e32 v194, v194
	v_cvt_f32_ubyte0_e32 v195, v188
	v_cvt_f32_ubyte1_e32 v243, v188
	v_cndmask_b32_e64 v194, v194, v203, s[38:39]
	v_mul_f32_e32 v194, v195, v194
	v_cvt_f32_ubyte1_e32 v195, v192
	v_rcp_f32_e32 v195, v195
	v_cvt_f32_ubyte2_e32 v244, v188
	v_cndmask_b32_e64 v195, v195, v203, s[38:39]
	v_mul_f32_e32 v195, v243, v195
	v_cvt_f32_ubyte2_e32 v243, v192
	v_rcp_f32_e32 v243, v243
	v_cvt_f32_ubyte3_e32 v192, v192
	v_cvt_f32_ubyte3_e32 v188, v188
	v_cndmask_b32_e64 v243, v243, v203, s[38:39]
	v_mul_f32_e32 v243, v244, v243
	v_rcp_f32_e32 v244, v192
	v_mul_f32_e32 v192, v64, v243
	v_cvt_f32_ubyte1_e32 v245, v189
	v_cndmask_b32_e64 v243, v244, v203, s[38:39]
	v_mul_f32_e32 v188, v188, v243
	v_cvt_f32_ubyte0_e32 v243, v193
	v_rcp_f32_e32 v243, v243
	v_cvt_f32_ubyte0_e32 v244, v189
	v_cndmask_b32_e64 v243, v243, v203, s[38:39]
	v_mul_f32_e32 v243, v244, v243
	v_cvt_f32_ubyte1_e32 v244, v193
	v_rcp_f32_e32 v244, v244
	v_cvt_f32_ubyte2_e32 v246, v189
	v_lshlrev_b64 v[190:191], 11, v[190:191]
	v_cndmask_b32_e64 v244, v244, v203, s[38:39]
	v_mul_f32_e32 v244, v245, v244
	v_cvt_f32_ubyte2_e32 v245, v193
	v_rcp_f32_e32 v245, v245
	v_cvt_f32_ubyte3_e32 v193, v193
	v_cvt_f32_ubyte3_e32 v189, v189
	v_cndmask_b32_e64 v245, v245, v203, s[38:39]
	v_mul_f32_e32 v245, v246, v245
	v_rcp_f32_e32 v246, v193
	v_lshl_add_u64 v[190:191], s[12:13], 0, v[190:191]
	v_mul_f32_e32 v193, v60, v245
	v_cndmask_b32_e64 v245, v246, v203, s[38:39]
	v_lshl_add_u64 v[190:191], v[190:191], 0, s[30:31]
	v_mul_f32_e32 v189, v189, v245
	v_lshl_add_u64 v[190:191], v[190:191], 0, v[0:1]
	v_mul_f32_e32 v194, v62, v194
	v_mul_f32_e32 v195, v63, v195
	v_mul_f32_e32 v188, v65, v188
	v_mul_f32_e32 v243, v58, v243
	v_mul_f32_e32 v244, v59, v244
	s_and_b64 vcc, exec, s[40:41]
	v_mul_f32_e32 v189, v61, v189
	s_cbranch_vccnz .LBB0_82
	v_cvt_pk_bf16_f32 v246, v194, v195
	v_cvt_pk_bf16_f32 v247, v192, v188
	v_cvt_pk_bf16_f32 v248, v243, v244
	v_cvt_pk_bf16_f32 v249, v193, v189
	global_store_dwordx4 v[190:191], v[246:249], off
	s_branch .LBB0_83
